# FFN-in GEMM: epilogue scale loads issued before the K-loop so the epilogue does not drain the next unit's prefetch
# baseline (speedup 1.0000x reference)
.LBB0_2023:
	v_mov_b32_e32 v161, 0
	s_andn2_b64 vcc, exec, s[18:19]
	v_mov_b32_e32 v160, 0
	v_mov_b32_e32 v159, 0
	v_mov_b32_e32 v158, 0
	v_mov_b32_e32 v163, 0
	v_mov_b32_e32 v162, 0
	v_mov_b32_e32 v157, 0
	v_mov_b32_e32 v156, 0
	v_mov_b32_e32 v127, 0
	v_mov_b32_e32 v126, 0
	v_mov_b32_e32 v123, 0
	v_mov_b32_e32 v122, 0
	v_mov_b32_e32 v125, 0
	v_mov_b32_e32 v124, 0
	v_mov_b32_e32 v121, 0
	v_mov_b32_e32 v120, 0
	v_mov_b32_e32 v103, 0
	v_mov_b32_e32 v102, 0
	v_mov_b32_e32 v97, 0
	v_mov_b32_e32 v96, 0
	v_mov_b32_e32 v99, 0
	v_mov_b32_e32 v98, 0
	v_mov_b32_e32 v95, 0
	v_mov_b32_e32 v94, 0
	v_mov_b32_e32 v87, 0
	v_mov_b32_e32 v86, 0
	v_mov_b32_e32 v81, 0
	v_mov_b32_e32 v80, 0
	v_mov_b32_e32 v83, 0
	v_mov_b32_e32 v82, 0
	v_mov_b32_e32 v79, 0
	v_mov_b32_e32 v78, 0
	v_mov_b32_e32 v171, 0
	v_mov_b32_e32 v170, 0
	v_mov_b32_e32 v167, 0
	v_mov_b32_e32 v166, 0
	v_mov_b32_e32 v169, 0
	v_mov_b32_e32 v168, 0
	v_mov_b32_e32 v165, 0
	v_mov_b32_e32 v164, 0
	v_mov_b32_e32 v153, 0
	v_mov_b32_e32 v152, 0
	v_mov_b32_e32 v149, 0
	v_mov_b32_e32 v148, 0
	v_mov_b32_e32 v151, 0
	v_mov_b32_e32 v150, 0
	v_mov_b32_e32 v129, 0
	v_mov_b32_e32 v128, 0
	v_mov_b32_e32 v115, 0
	v_mov_b32_e32 v114, 0
	v_mov_b32_e32 v111, 0
	v_mov_b32_e32 v110, 0
	v_mov_b32_e32 v113, 0
	v_mov_b32_e32 v112, 0
	v_mov_b32_e32 v109, 0
	v_mov_b32_e32 v108, 0
	v_mov_b32_e32 v93, 0
	v_mov_b32_e32 v92, 0
	v_mov_b32_e32 v89, 0
	v_mov_b32_e32 v88, 0
	v_mov_b32_e32 v91, 0
	v_mov_b32_e32 v90, 0
	v_mov_b32_e32 v85, 0
	v_mov_b32_e32 v84, 0
	v_mov_b32_e32 v69, 0
	v_mov_b32_e32 v68, 0
	v_mov_b32_e32 v67, 0
	v_mov_b32_e32 v66, 0
	v_mov_b32_e32 v65, 0
	v_mov_b32_e32 v64, 0
	v_mov_b32_e32 v63, 0
	v_mov_b32_e32 v62, 0
	v_mov_b32_e32 v55, 0
	v_mov_b32_e32 v54, 0
	v_mov_b32_e32 v49, 0
	v_mov_b32_e32 v48, 0
	v_mov_b32_e32 v51, 0
	v_mov_b32_e32 v50, 0
	v_mov_b32_e32 v47, 0
	v_mov_b32_e32 v46, 0
	v_mov_b32_e32 v33, 0
	v_mov_b32_e32 v32, 0
	v_mov_b32_e32 v25, 0
	v_mov_b32_e32 v24, 0
	v_mov_b32_e32 v31, 0
	v_mov_b32_e32 v30, 0
	v_mov_b32_e32 v23, 0
	v_mov_b32_e32 v22, 0
	v_mov_b32_e32 v17, 0
	v_mov_b32_e32 v16, 0
	v_mov_b32_e32 v13, 0
	v_mov_b32_e32 v12, 0
	v_mov_b32_e32 v15, 0
	v_mov_b32_e32 v14, 0
	v_mov_b32_e32 v11, 0
	v_mov_b32_e32 v10, 0
	v_mov_b32_e32 v77, 0
	v_mov_b32_e32 v76, 0
	v_mov_b32_e32 v73, 0
	v_mov_b32_e32 v72, 0
	v_mov_b32_e32 v75, 0
	v_mov_b32_e32 v74, 0
	v_mov_b32_e32 v71, 0
	v_mov_b32_e32 v70, 0
	v_mov_b32_e32 v61, 0
	v_mov_b32_e32 v60, 0
	v_mov_b32_e32 v57, 0
	v_mov_b32_e32 v56, 0
	v_mov_b32_e32 v59, 0
	v_mov_b32_e32 v58, 0
	v_mov_b32_e32 v53, 0
	v_mov_b32_e32 v52, 0
	v_mov_b32_e32 v41, 0
	v_mov_b32_e32 v40, 0
	v_mov_b32_e32 v37, 0
	v_mov_b32_e32 v36, 0
	v_mov_b32_e32 v39, 0
	v_mov_b32_e32 v38, 0
	v_mov_b32_e32 v35, 0
	v_mov_b32_e32 v34, 0
	v_mov_b32_e32 v9, 0
	v_mov_b32_e32 v8, 0
	v_mov_b32_e32 v7, 0
	v_mov_b32_e32 v6, 0
	v_mov_b32_e32 v5, 0
	v_mov_b32_e32 v4, 0
	v_mov_b32_e32 v3, 0
	v_mov_b32_e32 v2, 0
	s_cbranch_vccnz .LBB0_2027
	s_add_u32 s28, s28, 0x80
	s_addc_u32 s29, s29, 0
	s_add_u32 s63, s30, 0x100
	s_addc_u32 s64, s31, 0
	s_mov_b32 s30, 0
	v_mov_b32_e32 v2, 0
	v_mov_b32_e32 v3, 0
	v_mov_b32_e32 v4, 0
	v_mov_b32_e32 v5, 0
	v_mov_b32_e32 v6, 0
	v_mov_b32_e32 v7, 0
	v_mov_b32_e32 v8, 0
	v_mov_b32_e32 v9, 0
	v_mov_b32_e32 v10, 0
	v_mov_b32_e32 v11, 0
	v_mov_b32_e32 v12, 0
	v_mov_b32_e32 v13, 0
	v_mov_b32_e32 v14, 0
	v_mov_b32_e32 v15, 0
	v_mov_b32_e32 v16, 0
	v_mov_b32_e32 v17, 0
	v_mov_b32_e32 v22, 0
	v_mov_b32_e32 v23, 0
	v_mov_b32_e32 v24, 0
	v_mov_b32_e32 v25, 0
	v_mov_b32_e32 v30, 0
	v_mov_b32_e32 v31, 0
	v_mov_b32_e32 v32, 0
	v_mov_b32_e32 v33, 0
	v_mov_b32_e32 v38, 0
	v_mov_b32_e32 v39, 0
	v_mov_b32_e32 v40, 0
	v_mov_b32_e32 v41, 0
	v_mov_b32_e32 v46, 0
	v_mov_b32_e32 v47, 0
	v_mov_b32_e32 v48, 0
	v_mov_b32_e32 v49, 0
	v_mov_b32_e32 v18, 0
	v_mov_b32_e32 v19, 0
	v_mov_b32_e32 v20, 0
	v_mov_b32_e32 v21, 0
	v_mov_b32_e32 v26, 0
	v_mov_b32_e32 v27, 0
	v_mov_b32_e32 v28, 0
	v_mov_b32_e32 v29, 0
	v_mov_b32_e32 v34, 0
	v_mov_b32_e32 v35, 0
	v_mov_b32_e32 v36, 0
	v_mov_b32_e32 v37, 0
	v_mov_b32_e32 v42, 0
	v_mov_b32_e32 v43, 0
	v_mov_b32_e32 v44, 0
	v_mov_b32_e32 v45, 0
	v_mov_b32_e32 v50, 0
	v_mov_b32_e32 v51, 0
	v_mov_b32_e32 v52, 0
	v_mov_b32_e32 v53, 0
	v_mov_b32_e32 v54, 0
	v_mov_b32_e32 v55, 0
	v_mov_b32_e32 v56, 0
	v_mov_b32_e32 v57, 0
	v_mov_b32_e32 v58, 0
	v_mov_b32_e32 v59, 0
	v_mov_b32_e32 v60, 0
	v_mov_b32_e32 v61, 0
	v_mov_b32_e32 v62, 0
	v_mov_b32_e32 v63, 0
	v_mov_b32_e32 v64, 0
	v_mov_b32_e32 v65, 0
	v_mov_b32_e32 v66, 0
	v_mov_b32_e32 v67, 0
	v_mov_b32_e32 v68, 0
	v_mov_b32_e32 v69, 0
	v_mov_b32_e32 v70, 0
	v_mov_b32_e32 v71, 0
	v_mov_b32_e32 v72, 0
	v_mov_b32_e32 v73, 0
	v_mov_b32_e32 v74, 0
	v_mov_b32_e32 v75, 0
	v_mov_b32_e32 v76, 0
	v_mov_b32_e32 v77, 0
	v_mov_b32_e32 v78, 0
	v_mov_b32_e32 v79, 0
	v_mov_b32_e32 v80, 0
	v_mov_b32_e32 v81, 0
	v_mov_b32_e32 v86, 0
	v_mov_b32_e32 v87, 0
	v_mov_b32_e32 v88, 0
	v_mov_b32_e32 v89, 0
	v_mov_b32_e32 v94, 0
	v_mov_b32_e32 v95, 0
	v_mov_b32_e32 v96, 0
	v_mov_b32_e32 v97, 0
	v_mov_b32_e32 v102, 0
	v_mov_b32_e32 v103, 0
	v_mov_b32_e32 v104, 0
	v_mov_b32_e32 v105, 0
	v_mov_b32_e32 v110, 0
	v_mov_b32_e32 v111, 0
	v_mov_b32_e32 v112, 0
	v_mov_b32_e32 v113, 0
	v_mov_b32_e32 v82, 0
	v_mov_b32_e32 v83, 0
	v_mov_b32_e32 v84, 0
	v_mov_b32_e32 v85, 0
	v_mov_b32_e32 v90, 0
	v_mov_b32_e32 v91, 0
	v_mov_b32_e32 v92, 0
	v_mov_b32_e32 v93, 0
	v_mov_b32_e32 v98, 0
	v_mov_b32_e32 v99, 0
	v_mov_b32_e32 v100, 0
	v_mov_b32_e32 v101, 0
	v_mov_b32_e32 v106, 0
	v_mov_b32_e32 v107, 0
	v_mov_b32_e32 v108, 0
	v_mov_b32_e32 v109, 0
	v_mov_b32_e32 v114, 0
	v_mov_b32_e32 v115, 0
	v_mov_b32_e32 v116, 0
	v_mov_b32_e32 v117, 0
	v_mov_b32_e32 v118, 0
	v_mov_b32_e32 v119, 0
	v_mov_b32_e32 v120, 0
	v_mov_b32_e32 v121, 0
	v_mov_b32_e32 v122, 0
	v_mov_b32_e32 v123, 0
	v_mov_b32_e32 v124, 0
	v_mov_b32_e32 v125, 0
	v_mov_b32_e32 v126, 0
	v_mov_b32_e32 v127, 0
	v_mov_b32_e32 v128, 0
	v_mov_b32_e32 v129, 0
	s_lshl_b32 s98, s61, 8
	s_add_i32 s98, s98, s50
	s_lshl_b32 s100, s62, 7
	s_ashr_i32 s101, s100, 31
	s_lshl_b64 s[100:101], s[100:101], 2
	s_add_u32 s100, s45, s100
	s_addc_u32 s101, s46, s101
	v_lshrrev_b32_e32 v252, 1, v0
	v_and_or_b32 v252, v252, 24, s51
	v_lshlrev_b32_e32 v252, 2, v252
	v_and_or_b32 v254, v0, 15, s98
	v_add_u32_e32 v253, s53, v252
	v_lshlrev_b32_e32 v254, 2, v254
	global_load_dwordx4 v[228:231], v252, s[100:101] offset:16
	global_load_dwordx4 v[238:241], v252, s[100:101]
	global_load_dwordx4 v[242:245], v253, s[100:101] offset:3072
	s_add_u32 s100, s100, s24
	s_addc_u32 s101, s101, s25
	global_load_dwordx4 v[246:249], v252, s[100:101] offset:16
	global_load_dword v232, v254, s[14:15]
	global_load_dword v233, v254, s[14:15] offset:512
	global_load_dword v250, v254, s[14:15] offset:576
	global_load_dword v251, v254, s[14:15] offset:640
	global_load_dword v252, v254, s[14:15] offset:64
	global_load_dword v253, v254, s[14:15] offset:128
	global_load_dword v255, v254, s[14:15] offset:192
	global_load_dword v254, v254, s[14:15] offset:704

.LBB0_2029:
	s_lshl_b32 s28, s61, 8
	s_add_i32 s61, s28, s50
	s_lshl_b32 s28, s62, 7
	v_mov_b32_e32 v100, v0
	s_ashr_i32 s29, s28, 31
	s_lshl_b64 s[30:31], s[28:29], 2
	v_lshrrev_b32_e32 v18, 1, v100
	v_and_or_b32 v138, v18, 24, s51
	s_add_u32 s30, s45, s30
	s_addc_u32 s31, s46, s31
	v_lshlrev_b32_e32 v18, 2, v138
	v_mov_b32_e32 v19, v139
	v_mov_b64_e32 v[26:27], v[228:229]
	v_mov_b64_e32 v[28:29], v[230:231]
	v_mov_b64_e32 v[42:43], v[238:239]
	v_mov_b64_e32 v[44:45], v[240:241]
	v_lshl_add_u64 v[18:19], s[30:31], 0, v[18:19]
	v_lshl_add_u64 v[20:21], v[18:19], 0, s[24:25]
	v_add_co_u32_e32 v18, vcc, s53, v18
	v_and_or_b32 v188, v100, 15, s61
	s_nop 0
	v_addc_co_u32_e32 v19, vcc, 0, v19, vcc
	v_ashrrev_i32_e32 v189, 31, v188
	v_mov_b64_e32 v[104:105], v[242:243]
	v_mov_b64_e32 v[106:107], v[244:245]
	v_mov_b64_e32 v[184:185], v[246:247]
	v_mov_b64_e32 v[186:187], v[248:249]
	v_lshl_add_u64 v[20:21], v[188:189], 2, s[14:15]
	v_mov_b32_e32 v116, v232
	v_or_b32_e32 v178, 32, v188
	v_or_b32_e32 v182, 16, v188
	v_or_b32_e32 v174, 48, v188
	v_ashrrev_i32_e32 v179, 31, v178
	v_ashrrev_i32_e32 v183, 31, v182
	v_ashrrev_i32_e32 v175, 31, v174
	v_lshl_add_u64 v[180:181], v[178:179], 2, s[14:15]
	v_lshl_add_u64 v[100:101], v[182:183], 2, s[14:15]
	v_lshl_add_u64 v[190:191], v[174:175], 2, s[14:15]
	v_mov_b32_e32 v172, v233
	v_mov_b32_e32 v154, v250
	v_mov_b32_e32 v118, v251
	v_mov_b32_e32 v192, v252
	s_nop 0
	v_mov_b32_e32 v180, v253
	s_nop 0
	v_mov_b32_e32 v176, v255
	v_mov_b32_e32 v18, v254
	v_add_u32_e32 v177, 0x80, v188
	v_add_u32_e32 v173, 0x90, v188
	v_add_u32_e32 v119, 0xa0, v188
	v_add_u32_e32 v19, 0xb0, v188
	s_and_b64 vcc, exec, s[0:1]
	s_mov_b64 s[0:1], -1
	v_pk_mul_f32 v[28:29], v[28:29], s[22:23] op_sel_hi:[1,0]
	v_pk_mul_f32 v[100:101], v[44:45], s[22:23] op_sel_hi:[1,0]
	v_pk_mul_f32 v[44:45], v[42:43], s[22:23] op_sel_hi:[1,0]
	v_pk_mul_f32 v[26:27], v[26:27], s[22:23] op_sel_hi:[1,0]
	v_pk_mul_f32 v[158:159], v[44:45], v[158:159]
	v_pk_mul_f32 v[160:161], v[100:101], v[160:161]
	v_pk_mul_f32 v[162:163], v[28:29], v[162:163]
	v_pk_mul_f32 v[156:157], v[26:27], v[156:157]
	v_pk_mul_f32 v[126:127], v[100:101], v[126:127]
	v_pk_mul_f32 v[106:107], v[106:107], s[22:23] op_sel_hi:[1,0]
	v_pk_mul_f32 v[104:105], v[104:105], s[22:23] op_sel_hi:[1,0]
	v_pk_mul_f32 v[42:43], v[186:187], s[22:23] op_sel_hi:[1,0]
	v_pk_mul_f32 v[20:21], v[184:185], s[22:23] op_sel_hi:[1,0]
	v_pk_mul_f32 v[158:159], v[158:159], v[116:117] op_sel_hi:[1,0]
	v_pk_mul_f32 v[170:171], v[106:107], v[170:171]
	v_pk_mul_f32 v[166:167], v[104:105], v[166:167]
	v_pk_mul_f32 v[168:169], v[42:43], v[168:169]
	v_pk_mul_f32 v[164:165], v[20:21], v[164:165]
	v_mul_f32_e32 v175, 0xbfb8aa3b, v158
	v_mul_f32_e32 v179, 0xbfb8aa3b, v159
	v_pk_mul_f32 v[160:161], v[160:161], v[116:117] op_sel_hi:[1,0]
	v_pk_mul_f32 v[162:163], v[162:163], v[116:117] op_sel_hi:[1,0]
	v_pk_mul_f32 v[156:157], v[156:157], v[116:117] op_sel_hi:[1,0]
	v_pk_mul_f32 v[170:171], v[170:171], v[116:117] op_sel_hi:[1,0]
	v_pk_mul_f32 v[166:167], v[166:167], v[116:117] op_sel_hi:[1,0]
	v_pk_mul_f32 v[164:165], v[164:165], v[116:117] op_sel_hi:[1,0]
	v_pk_mul_f32 v[116:117], v[168:169], v[116:117] op_sel_hi:[1,0]
	v_exp_f32_e32 v168, v175
	v_exp_f32_e32 v169, v179
	v_mul_f32_e32 v181, 0xbfb8aa3b, v160
	v_mul_f32_e32 v183, 0xbfb8aa3b, v161
	v_add_f32_e32 v168, 1.0, v168
	v_add_f32_e32 v169, 1.0, v169
	v_rcp_f32_e32 v168, v168
	v_rcp_f32_e32 v169, v169
	v_mul_f32_e32 v184, 0xbfb8aa3b, v156
	v_mul_f32_e32 v185, 0xbfb8aa3b, v157
	v_exp_f32_e32 v175, v181
	v_exp_f32_e32 v179, v183
	v_exp_f32_e32 v181, v184
	v_exp_f32_e32 v183, v185
	v_pk_mul_f32 v[158:159], v[158:159], v[168:169]
	v_mul_f32_e32 v186, 0xbfb8aa3b, v162
	v_add_f32_e32 v175, 1.0, v175
	v_pk_mul_f32 v[158:159], v[166:167], v[158:159]
	v_mul_f32_e32 v166, 0xbfb8aa3b, v163
	v_exp_f32_e32 v189, v186
	v_add_f32_e32 v181, 1.0, v181
	v_rcp_f32_e32 v184, v175
	v_add_f32_e32 v175, 1.0, v183
	v_exp_f32_e32 v167, v166
	v_rcp_f32_e32 v186, v181
	v_rcp_f32_e32 v187, v175
	v_add_f32_e32 v179, 1.0, v179
	v_add_f32_e32 v166, 1.0, v189
	v_add_f32_e32 v167, 1.0, v167
	v_rcp_f32_e32 v185, v179
	v_rcp_f32_e32 v166, v166
	v_rcp_f32_e32 v167, v167
	v_pk_mul_f32 v[156:157], v[156:157], v[186:187]
	v_pk_mul_f32 v[160:161], v[160:161], v[184:185]
	v_pk_mul_f32 v[156:157], v[164:165], v[156:157]
	v_mov_b32_e32 v164, v139
	v_mov_b32_e32 v165, v139
	v_cvt_pk_fp8_f32 v164, v158, v159
	v_cvt_pk_fp8_f32 v165, v156, v157
	v_pk_mul_f32 v[156:157], v[162:163], v[166:167]
	v_pk_mul_f32 v[126:127], v[126:127], v[192:193] op_sel_hi:[1,0]
	v_pk_mul_f32 v[160:161], v[170:171], v[160:161]
	v_pk_mul_f32 v[116:117], v[116:117], v[156:157]
	v_mul_f32_e32 v158, 0xbfb8aa3b, v126
	v_mul_f32_e32 v159, 0xbfb8aa3b, v127
	v_cvt_pk_fp8_f32 v164, v160, v161 op_sel:[0,0,1]
	v_cvt_pk_fp8_f32 v165, v116, v117 op_sel:[0,0,1]
	v_mov_b64_e32 v[116:117], s[12:13]
	v_exp_f32_e32 v158, v158
	v_exp_f32_e32 v159, v159
	v_mad_i64_i32 v[156:157], s[30:31], v188, s58, v[116:117]
	v_lshl_add_u64 v[156:157], v[156:157], 0, s[28:29]
	v_pk_mul_f32 v[122:123], v[44:45], v[122:123]
	v_lshl_add_u64 v[156:157], v[156:157], 0, v[138:139]
	v_pk_mul_f32 v[122:123], v[122:123], v[192:193] op_sel_hi:[1,0]
	global_store_dwordx2 v[156:157], v[164:165], off
	v_mul_f32_e32 v156, 0xbfb8aa3b, v122
	v_mul_f32_e32 v157, 0xbfb8aa3b, v123
	v_add_f32_e32 v158, 1.0, v158
	v_add_f32_e32 v159, 1.0, v159
	v_exp_f32_e32 v156, v156
	v_exp_f32_e32 v157, v157
	v_rcp_f32_e32 v158, v158
	v_rcp_f32_e32 v159, v159
	v_pk_mul_f32 v[120:121], v[26:27], v[120:121]
	v_pk_mul_f32 v[152:153], v[106:107], v[152:153]
	v_pk_mul_f32 v[120:121], v[120:121], v[192:193] op_sel_hi:[1,0]
	v_pk_mul_f32 v[152:153], v[152:153], v[192:193] op_sel_hi:[1,0]
	v_add_f32_e32 v156, 1.0, v156
	v_add_f32_e32 v157, 1.0, v157
	v_pk_mul_f32 v[126:127], v[126:127], v[158:159]
	v_rcp_f32_e32 v156, v156
	v_rcp_f32_e32 v157, v157
	v_pk_mul_f32 v[126:127], v[152:153], v[126:127]
	v_mul_f32_e32 v152, 0xbfb8aa3b, v120
	v_mul_f32_e32 v153, 0xbfb8aa3b, v121
	v_exp_f32_e32 v152, v152
	v_exp_f32_e32 v153, v153
	v_pk_mul_f32 v[124:125], v[28:29], v[124:125]
	v_pk_mul_f32 v[148:149], v[104:105], v[148:149]
	v_pk_mul_f32 v[124:125], v[124:125], v[192:193] op_sel_hi:[1,0]
	v_pk_mul_f32 v[148:149], v[148:149], v[192:193] op_sel_hi:[1,0]
	v_pk_mul_f32 v[122:123], v[122:123], v[156:157]
	v_pk_mul_f32 v[128:129], v[20:21], v[128:129]
	v_pk_mul_f32 v[122:123], v[148:149], v[122:123]
	v_add_f32_e32 v148, 1.0, v152
	v_add_f32_e32 v149, 1.0, v153
	v_mul_f32_e32 v152, 0xbfb8aa3b, v124
	v_mul_f32_e32 v153, 0xbfb8aa3b, v125
	v_exp_f32_e32 v152, v152
	v_exp_f32_e32 v153, v153
	v_rcp_f32_e32 v148, v148
	v_rcp_f32_e32 v149, v149
	v_add_f32_e32 v152, 1.0, v152
	v_add_f32_e32 v153, 1.0, v153
	v_pk_mul_f32 v[128:129], v[128:129], v[192:193] op_sel_hi:[1,0]
	v_rcp_f32_e32 v152, v152
	v_rcp_f32_e32 v153, v153
	v_pk_mul_f32 v[120:121], v[120:121], v[148:149]
	v_pk_mul_f32 v[150:151], v[42:43], v[150:151]
	v_pk_mul_f32 v[120:121], v[128:129], v[120:121]
	v_mov_b32_e32 v128, v139
	v_mov_b32_e32 v129, v139
	v_cvt_pk_fp8_f32 v128, v122, v123
	v_cvt_pk_fp8_f32 v129, v120, v121
	v_pk_mul_f32 v[102:103], v[100:101], v[102:103]
	v_pk_mul_f32 v[150:151], v[150:151], v[192:193] op_sel_hi:[1,0]
	v_pk_mul_f32 v[120:121], v[124:125], v[152:153]
	v_pk_mul_f32 v[102:103], v[102:103], v[180:181] op_sel_hi:[1,0]
	v_pk_mul_f32 v[120:121], v[150:151], v[120:121]
	v_mul_f32_e32 v122, 0xbfb8aa3b, v102
	v_mul_f32_e32 v123, 0xbfb8aa3b, v103
	v_cvt_pk_fp8_f32 v128, v126, v127 op_sel:[0,0,1]
	v_cvt_pk_fp8_f32 v129, v120, v121 op_sel:[0,0,1]
	v_exp_f32_e32 v122, v122
	v_exp_f32_e32 v123, v123
	v_mad_i64_i32 v[120:121], s[30:31], v182, s58, v[116:117]
	v_lshl_add_u64 v[120:121], v[120:121], 0, s[28:29]
	v_pk_mul_f32 v[96:97], v[44:45], v[96:97]
	v_lshl_add_u64 v[120:121], v[120:121], 0, v[138:139]
	v_pk_mul_f32 v[96:97], v[96:97], v[180:181] op_sel_hi:[1,0]
	global_store_dwordx2 v[120:121], v[128:129], off
	v_mul_f32_e32 v120, 0xbfb8aa3b, v96
	v_mul_f32_e32 v121, 0xbfb8aa3b, v97
	v_add_f32_e32 v122, 1.0, v122
	v_add_f32_e32 v123, 1.0, v123
	v_exp_f32_e32 v120, v120
	v_exp_f32_e32 v121, v121
	v_rcp_f32_e32 v122, v122
	v_rcp_f32_e32 v123, v123
	v_pk_mul_f32 v[94:95], v[26:27], v[94:95]
	v_pk_mul_f32 v[114:115], v[106:107], v[114:115]
	v_pk_mul_f32 v[94:95], v[94:95], v[180:181] op_sel_hi:[1,0]
	v_pk_mul_f32 v[114:115], v[114:115], v[180:181] op_sel_hi:[1,0]
	v_add_f32_e32 v120, 1.0, v120
	v_add_f32_e32 v121, 1.0, v121
	v_pk_mul_f32 v[102:103], v[102:103], v[122:123]
	v_rcp_f32_e32 v120, v120
	v_rcp_f32_e32 v121, v121
	v_pk_mul_f32 v[102:103], v[114:115], v[102:103]
	v_mul_f32_e32 v114, 0xbfb8aa3b, v94
	v_mul_f32_e32 v115, 0xbfb8aa3b, v95
	v_exp_f32_e32 v114, v114
	v_exp_f32_e32 v115, v115
	v_pk_mul_f32 v[98:99], v[28:29], v[98:99]
	v_pk_mul_f32 v[110:111], v[104:105], v[110:111]
	v_pk_mul_f32 v[98:99], v[98:99], v[180:181] op_sel_hi:[1,0]
	v_pk_mul_f32 v[110:111], v[110:111], v[180:181] op_sel_hi:[1,0]
	v_pk_mul_f32 v[96:97], v[96:97], v[120:121]
	v_pk_mul_f32 v[108:109], v[20:21], v[108:109]
	v_pk_mul_f32 v[96:97], v[110:111], v[96:97]
	v_add_f32_e32 v110, 1.0, v114
	v_add_f32_e32 v111, 1.0, v115
	v_mul_f32_e32 v114, 0xbfb8aa3b, v98
	v_mul_f32_e32 v115, 0xbfb8aa3b, v99
	v_exp_f32_e32 v114, v114
	v_exp_f32_e32 v115, v115
	v_rcp_f32_e32 v110, v110
	v_rcp_f32_e32 v111, v111
	v_add_f32_e32 v114, 1.0, v114
	v_add_f32_e32 v115, 1.0, v115
	v_pk_mul_f32 v[108:109], v[108:109], v[180:181] op_sel_hi:[1,0]
	v_rcp_f32_e32 v114, v114
	v_rcp_f32_e32 v115, v115
	v_pk_mul_f32 v[94:95], v[94:95], v[110:111]
	v_pk_mul_f32 v[112:113], v[42:43], v[112:113]
	v_pk_mul_f32 v[94:95], v[108:109], v[94:95]
	v_mov_b32_e32 v108, v139
	v_mov_b32_e32 v109, v139
	v_cvt_pk_fp8_f32 v108, v96, v97
	v_cvt_pk_fp8_f32 v109, v94, v95
	v_pk_mul_f32 v[86:87], v[100:101], v[86:87]
	v_pk_mul_f32 v[112:113], v[112:113], v[180:181] op_sel_hi:[1,0]
	v_pk_mul_f32 v[94:95], v[98:99], v[114:115]
	v_pk_mul_f32 v[86:87], v[86:87], v[176:177] op_sel_hi:[1,0]
	v_pk_mul_f32 v[94:95], v[112:113], v[94:95]
	v_mul_f32_e32 v96, 0xbfb8aa3b, v86
	v_mul_f32_e32 v97, 0xbfb8aa3b, v87
	v_cvt_pk_fp8_f32 v108, v102, v103 op_sel:[0,0,1]
	v_cvt_pk_fp8_f32 v109, v94, v95 op_sel:[0,0,1]
	v_exp_f32_e32 v96, v96
	v_exp_f32_e32 v97, v97
	v_mad_i64_i32 v[94:95], s[30:31], v178, s58, v[116:117]
	v_lshl_add_u64 v[94:95], v[94:95], 0, s[28:29]
	v_pk_mul_f32 v[80:81], v[44:45], v[80:81]
	v_lshl_add_u64 v[94:95], v[94:95], 0, v[138:139]
	v_pk_mul_f32 v[80:81], v[80:81], v[176:177] op_sel_hi:[1,0]
	global_store_dwordx2 v[94:95], v[108:109], off
	v_mul_f32_e32 v94, 0xbfb8aa3b, v80
	v_mul_f32_e32 v95, 0xbfb8aa3b, v81
	v_add_f32_e32 v96, 1.0, v96
	v_add_f32_e32 v97, 1.0, v97
	v_exp_f32_e32 v94, v94
	v_exp_f32_e32 v95, v95
	v_rcp_f32_e32 v96, v96
	v_rcp_f32_e32 v97, v97
	v_pk_mul_f32 v[78:79], v[26:27], v[78:79]
	v_pk_mul_f32 v[92:93], v[106:107], v[92:93]
	v_pk_mul_f32 v[78:79], v[78:79], v[176:177] op_sel_hi:[1,0]
	v_pk_mul_f32 v[92:93], v[92:93], v[176:177] op_sel_hi:[1,0]
	v_add_f32_e32 v94, 1.0, v94
	v_add_f32_e32 v95, 1.0, v95
	v_pk_mul_f32 v[86:87], v[86:87], v[96:97]
	v_rcp_f32_e32 v94, v94
	v_rcp_f32_e32 v95, v95
	v_pk_mul_f32 v[86:87], v[92:93], v[86:87]
	v_mul_f32_e32 v92, 0xbfb8aa3b, v78
	v_mul_f32_e32 v93, 0xbfb8aa3b, v79
	v_exp_f32_e32 v92, v92
	v_exp_f32_e32 v93, v93
	v_pk_mul_f32 v[82:83], v[28:29], v[82:83]
	v_pk_mul_f32 v[88:89], v[104:105], v[88:89]
	v_pk_mul_f32 v[82:83], v[82:83], v[176:177] op_sel_hi:[1,0]
	v_pk_mul_f32 v[88:89], v[88:89], v[176:177] op_sel_hi:[1,0]
	v_pk_mul_f32 v[80:81], v[80:81], v[94:95]
	v_pk_mul_f32 v[84:85], v[20:21], v[84:85]
	v_pk_mul_f32 v[80:81], v[88:89], v[80:81]
	v_add_f32_e32 v88, 1.0, v92
	v_add_f32_e32 v89, 1.0, v93
	v_mul_f32_e32 v92, 0xbfb8aa3b, v82
	v_mul_f32_e32 v93, 0xbfb8aa3b, v83
	v_exp_f32_e32 v92, v92
	v_exp_f32_e32 v93, v93
	v_rcp_f32_e32 v88, v88
	v_rcp_f32_e32 v89, v89
	v_add_f32_e32 v92, 1.0, v92
	v_add_f32_e32 v93, 1.0, v93
	v_pk_mul_f32 v[84:85], v[84:85], v[176:177] op_sel_hi:[1,0]
	v_rcp_f32_e32 v92, v92
	v_rcp_f32_e32 v93, v93
	v_pk_mul_f32 v[78:79], v[78:79], v[88:89]
	v_pk_mul_f32 v[90:91], v[42:43], v[90:91]
	v_pk_mul_f32 v[78:79], v[84:85], v[78:79]
	v_mov_b32_e32 v84, v139
	v_mov_b32_e32 v85, v139
	v_cvt_pk_fp8_f32 v84, v80, v81
	v_cvt_pk_fp8_f32 v85, v78, v79
	v_pk_mul_f32 v[68:69], v[100:101], v[68:69]
	v_pk_mul_f32 v[90:91], v[90:91], v[176:177] op_sel_hi:[1,0]
	v_pk_mul_f32 v[78:79], v[82:83], v[92:93]
	v_pk_mul_f32 v[68:69], v[68:69], v[172:173] op_sel_hi:[1,0]
	v_pk_mul_f32 v[78:79], v[90:91], v[78:79]
	v_mul_f32_e32 v80, 0xbfb8aa3b, v68
	v_mul_f32_e32 v81, 0xbfb8aa3b, v69
	v_cvt_pk_fp8_f32 v84, v86, v87 op_sel:[0,0,1]
	v_cvt_pk_fp8_f32 v85, v78, v79 op_sel:[0,0,1]
	v_exp_f32_e32 v80, v80
	v_exp_f32_e32 v81, v81
	v_mad_i64_i32 v[78:79], s[30:31], v174, s58, v[116:117]
	v_lshl_add_u64 v[78:79], v[78:79], 0, s[28:29]
	v_pk_mul_f32 v[66:67], v[44:45], v[66:67]
	v_lshl_add_u64 v[78:79], v[78:79], 0, v[138:139]
	v_pk_mul_f32 v[66:67], v[66:67], v[172:173] op_sel_hi:[1,0]
	global_store_dwordx2 v[78:79], v[84:85], off
	v_mul_f32_e32 v78, 0xbfb8aa3b, v66
	v_mul_f32_e32 v79, 0xbfb8aa3b, v67
	v_add_f32_e32 v80, 1.0, v80
	v_add_f32_e32 v81, 1.0, v81
	v_exp_f32_e32 v78, v78
	v_exp_f32_e32 v79, v79
	v_rcp_f32_e32 v80, v80
	v_rcp_f32_e32 v81, v81
	v_pk_mul_f32 v[62:63], v[26:27], v[62:63]
	v_pk_mul_f32 v[76:77], v[106:107], v[76:77]
	v_pk_mul_f32 v[62:63], v[62:63], v[172:173] op_sel_hi:[1,0]
	v_pk_mul_f32 v[76:77], v[76:77], v[172:173] op_sel_hi:[1,0]
	v_add_f32_e32 v78, 1.0, v78
	v_add_f32_e32 v79, 1.0, v79
	v_pk_mul_f32 v[68:69], v[68:69], v[80:81]
	v_rcp_f32_e32 v78, v78
	v_rcp_f32_e32 v79, v79
	v_pk_mul_f32 v[68:69], v[76:77], v[68:69]
	v_mul_f32_e32 v76, 0xbfb8aa3b, v62
	v_mul_f32_e32 v77, 0xbfb8aa3b, v63
	v_exp_f32_e32 v76, v76
	v_exp_f32_e32 v77, v77
	v_pk_mul_f32 v[64:65], v[28:29], v[64:65]
	v_pk_mul_f32 v[72:73], v[104:105], v[72:73]
	v_pk_mul_f32 v[64:65], v[64:65], v[172:173] op_sel_hi:[1,0]
	v_pk_mul_f32 v[72:73], v[72:73], v[172:173] op_sel_hi:[1,0]
	v_pk_mul_f32 v[66:67], v[66:67], v[78:79]
	v_pk_mul_f32 v[70:71], v[20:21], v[70:71]
	v_pk_mul_f32 v[66:67], v[72:73], v[66:67]
	v_add_f32_e32 v72, 1.0, v76
	v_add_f32_e32 v73, 1.0, v77
	v_mul_f32_e32 v76, 0xbfb8aa3b, v64
	v_mul_f32_e32 v77, 0xbfb8aa3b, v65
	v_exp_f32_e32 v76, v76
	v_exp_f32_e32 v77, v77
	v_rcp_f32_e32 v72, v72
	v_rcp_f32_e32 v73, v73
	v_add_f32_e32 v76, 1.0, v76
	v_add_f32_e32 v77, 1.0, v77
	v_pk_mul_f32 v[70:71], v[70:71], v[172:173] op_sel_hi:[1,0]
	v_rcp_f32_e32 v76, v76
	v_rcp_f32_e32 v77, v77
	v_pk_mul_f32 v[62:63], v[62:63], v[72:73]
	v_pk_mul_f32 v[74:75], v[42:43], v[74:75]
	v_pk_mul_f32 v[62:63], v[70:71], v[62:63]
	v_mov_b32_e32 v70, v139
	v_mov_b32_e32 v71, v139
	v_cvt_pk_fp8_f32 v70, v66, v67
	v_cvt_pk_fp8_f32 v71, v62, v63
	v_pk_mul_f32 v[54:55], v[100:101], v[54:55]
	v_pk_mul_f32 v[74:75], v[74:75], v[172:173] op_sel_hi:[1,0]
	v_pk_mul_f32 v[62:63], v[64:65], v[76:77]
	v_pk_mul_f32 v[54:55], v[54:55], v[154:155] op_sel_hi:[1,0]
	v_pk_mul_f32 v[62:63], v[74:75], v[62:63]
	v_mul_f32_e32 v64, 0xbfb8aa3b, v54
	v_mul_f32_e32 v65, 0xbfb8aa3b, v55
	v_cvt_pk_fp8_f32 v70, v68, v69 op_sel:[0,0,1]
	v_cvt_pk_fp8_f32 v71, v62, v63 op_sel:[0,0,1]
	v_exp_f32_e32 v64, v64
	v_exp_f32_e32 v65, v65
	v_mad_i64_i32 v[62:63], s[30:31], v177, s58, v[116:117]
	v_lshl_add_u64 v[62:63], v[62:63], 0, s[28:29]
	v_pk_mul_f32 v[48:49], v[44:45], v[48:49]
	v_lshl_add_u64 v[62:63], v[62:63], 0, v[138:139]
	v_pk_mul_f32 v[48:49], v[48:49], v[154:155] op_sel_hi:[1,0]
	global_store_dwordx2 v[62:63], v[70:71], off
	v_mul_f32_e32 v62, 0xbfb8aa3b, v48
	v_mul_f32_e32 v63, 0xbfb8aa3b, v49
	v_add_f32_e32 v64, 1.0, v64
	v_add_f32_e32 v65, 1.0, v65
	v_exp_f32_e32 v62, v62
	v_exp_f32_e32 v63, v63
	v_rcp_f32_e32 v64, v64
	v_rcp_f32_e32 v65, v65
	v_pk_mul_f32 v[46:47], v[26:27], v[46:47]
	v_pk_mul_f32 v[60:61], v[106:107], v[60:61]
	v_pk_mul_f32 v[46:47], v[46:47], v[154:155] op_sel_hi:[1,0]
	v_pk_mul_f32 v[60:61], v[60:61], v[154:155] op_sel_hi:[1,0]
	v_add_f32_e32 v62, 1.0, v62
	v_add_f32_e32 v63, 1.0, v63
	v_pk_mul_f32 v[54:55], v[54:55], v[64:65]
	v_rcp_f32_e32 v62, v62
	v_rcp_f32_e32 v63, v63
	v_pk_mul_f32 v[54:55], v[60:61], v[54:55]
	v_mul_f32_e32 v60, 0xbfb8aa3b, v46
	v_mul_f32_e32 v61, 0xbfb8aa3b, v47
	v_exp_f32_e32 v60, v60
	v_exp_f32_e32 v61, v61
	v_pk_mul_f32 v[50:51], v[28:29], v[50:51]
	v_pk_mul_f32 v[56:57], v[104:105], v[56:57]
	v_pk_mul_f32 v[50:51], v[50:51], v[154:155] op_sel_hi:[1,0]
	v_pk_mul_f32 v[56:57], v[56:57], v[154:155] op_sel_hi:[1,0]
	v_pk_mul_f32 v[48:49], v[48:49], v[62:63]
	v_pk_mul_f32 v[52:53], v[20:21], v[52:53]
	v_pk_mul_f32 v[48:49], v[56:57], v[48:49]
	v_add_f32_e32 v56, 1.0, v60
	v_add_f32_e32 v57, 1.0, v61
	v_mul_f32_e32 v60, 0xbfb8aa3b, v50
	v_mul_f32_e32 v61, 0xbfb8aa3b, v51
	v_exp_f32_e32 v60, v60
	v_exp_f32_e32 v61, v61
	v_rcp_f32_e32 v56, v56
	v_rcp_f32_e32 v57, v57
	v_add_f32_e32 v60, 1.0, v60
	v_add_f32_e32 v61, 1.0, v61
	v_pk_mul_f32 v[52:53], v[52:53], v[154:155] op_sel_hi:[1,0]
	v_rcp_f32_e32 v60, v60
	v_rcp_f32_e32 v61, v61
	v_pk_mul_f32 v[46:47], v[46:47], v[56:57]
	v_pk_mul_f32 v[58:59], v[42:43], v[58:59]
	v_pk_mul_f32 v[46:47], v[52:53], v[46:47]
	v_mov_b32_e32 v52, v139
	v_mov_b32_e32 v53, v139
	v_cvt_pk_fp8_f32 v52, v48, v49
	v_cvt_pk_fp8_f32 v53, v46, v47
	v_pk_mul_f32 v[32:33], v[100:101], v[32:33]
	v_pk_mul_f32 v[58:59], v[58:59], v[154:155] op_sel_hi:[1,0]
	v_pk_mul_f32 v[46:47], v[50:51], v[60:61]
	v_pk_mul_f32 v[32:33], v[32:33], v[118:119] op_sel_hi:[1,0]
	v_pk_mul_f32 v[46:47], v[58:59], v[46:47]
	v_mul_f32_e32 v48, 0xbfb8aa3b, v32
	v_mul_f32_e32 v49, 0xbfb8aa3b, v33
	v_cvt_pk_fp8_f32 v52, v54, v55 op_sel:[0,0,1]
	v_cvt_pk_fp8_f32 v53, v46, v47 op_sel:[0,0,1]
	v_exp_f32_e32 v48, v48
	v_exp_f32_e32 v49, v49
	v_mad_i64_i32 v[46:47], s[30:31], v173, s58, v[116:117]
	v_lshl_add_u64 v[46:47], v[46:47], 0, s[28:29]
	v_pk_mul_f32 v[24:25], v[44:45], v[24:25]
	v_lshl_add_u64 v[46:47], v[46:47], 0, v[138:139]
	v_pk_mul_f32 v[24:25], v[24:25], v[118:119] op_sel_hi:[1,0]
	global_store_dwordx2 v[46:47], v[52:53], off
	v_mul_f32_e32 v46, 0xbfb8aa3b, v24
	v_mul_f32_e32 v47, 0xbfb8aa3b, v25
	v_add_f32_e32 v48, 1.0, v48
	v_add_f32_e32 v49, 1.0, v49
	v_exp_f32_e32 v46, v46
	v_exp_f32_e32 v47, v47
	v_rcp_f32_e32 v48, v48
	v_rcp_f32_e32 v49, v49
	v_pk_mul_f32 v[22:23], v[26:27], v[22:23]
	v_pk_mul_f32 v[40:41], v[106:107], v[40:41]
	v_pk_mul_f32 v[22:23], v[22:23], v[118:119] op_sel_hi:[1,0]
	v_pk_mul_f32 v[40:41], v[40:41], v[118:119] op_sel_hi:[1,0]
	v_add_f32_e32 v46, 1.0, v46
	v_add_f32_e32 v47, 1.0, v47
	v_pk_mul_f32 v[32:33], v[32:33], v[48:49]
	v_rcp_f32_e32 v46, v46
	v_rcp_f32_e32 v47, v47
	v_pk_mul_f32 v[32:33], v[40:41], v[32:33]
	v_mul_f32_e32 v40, 0xbfb8aa3b, v22
	v_mul_f32_e32 v41, 0xbfb8aa3b, v23
	v_exp_f32_e32 v40, v40
	v_exp_f32_e32 v41, v41
	v_pk_mul_f32 v[30:31], v[28:29], v[30:31]
	v_pk_mul_f32 v[36:37], v[104:105], v[36:37]
	v_pk_mul_f32 v[30:31], v[30:31], v[118:119] op_sel_hi:[1,0]
	v_pk_mul_f32 v[36:37], v[36:37], v[118:119] op_sel_hi:[1,0]
	v_pk_mul_f32 v[24:25], v[24:25], v[46:47]
	v_pk_mul_f32 v[34:35], v[20:21], v[34:35]
	v_pk_mul_f32 v[24:25], v[36:37], v[24:25]
	v_add_f32_e32 v36, 1.0, v40
	v_add_f32_e32 v37, 1.0, v41
	v_mul_f32_e32 v40, 0xbfb8aa3b, v30
	v_mul_f32_e32 v41, 0xbfb8aa3b, v31
	v_exp_f32_e32 v40, v40
	v_exp_f32_e32 v41, v41
	v_rcp_f32_e32 v36, v36
	v_rcp_f32_e32 v37, v37
	v_add_f32_e32 v40, 1.0, v40
	v_add_f32_e32 v41, 1.0, v41
	v_pk_mul_f32 v[34:35], v[34:35], v[118:119] op_sel_hi:[1,0]
	v_rcp_f32_e32 v40, v40
	v_rcp_f32_e32 v41, v41
	v_pk_mul_f32 v[22:23], v[22:23], v[36:37]
	v_pk_mul_f32 v[38:39], v[42:43], v[38:39]
	v_pk_mul_f32 v[22:23], v[34:35], v[22:23]
	v_mov_b32_e32 v34, v139
	v_mov_b32_e32 v35, v139
	v_cvt_pk_fp8_f32 v34, v24, v25
	v_cvt_pk_fp8_f32 v35, v22, v23
	v_pk_mul_f32 v[38:39], v[38:39], v[118:119] op_sel_hi:[1,0]
	v_pk_mul_f32 v[22:23], v[30:31], v[40:41]
	v_cvt_pk_fp8_f32 v34, v32, v33 op_sel:[0,0,1]
	v_pk_mul_f32 v[22:23], v[38:39], v[22:23]
	v_pk_mul_f32 v[12:13], v[44:45], v[12:13]
	v_cvt_pk_fp8_f32 v35, v22, v23 op_sel:[0,0,1]
	v_mad_i64_i32 v[22:23], s[30:31], v119, s58, v[116:117]
	v_lshl_add_u64 v[22:23], v[22:23], 0, s[28:29]
	v_lshl_add_u64 v[22:23], v[22:23], 0, v[138:139]
	v_pk_mul_f32 v[12:13], v[12:13], v[18:19] op_sel_hi:[1,0]
	global_store_dwordx2 v[22:23], v[34:35], off
	v_mul_f32_e32 v22, 0xbfb8aa3b, v12
	v_mul_f32_e32 v23, 0xbfb8aa3b, v13
	v_exp_f32_e32 v22, v22
	v_exp_f32_e32 v23, v23
	v_pk_mul_f32 v[16:17], v[100:101], v[16:17]
	v_pk_mul_f32 v[2:3], v[20:21], v[2:3]
	v_pk_mul_f32 v[16:17], v[16:17], v[18:19] op_sel_hi:[1,0]
	v_add_f32_e32 v20, 1.0, v22
	v_add_f32_e32 v21, 1.0, v23
	v_mul_f32_e32 v22, 0xbfb8aa3b, v16
	v_mul_f32_e32 v23, 0xbfb8aa3b, v17
	v_exp_f32_e32 v22, v22
	v_exp_f32_e32 v23, v23
	v_pk_mul_f32 v[10:11], v[26:27], v[10:11]
	v_pk_mul_f32 v[8:9], v[106:107], v[8:9]
	v_add_f32_e32 v22, 1.0, v22
	v_add_f32_e32 v23, 1.0, v23
	v_rcp_f32_e32 v22, v22
	v_rcp_f32_e32 v23, v23
	v_pk_mul_f32 v[10:11], v[10:11], v[18:19] op_sel_hi:[1,0]
	v_pk_mul_f32 v[8:9], v[8:9], v[18:19] op_sel_hi:[1,0]
	v_rcp_f32_e32 v20, v20
	v_pk_mul_f32 v[16:17], v[16:17], v[22:23]
	v_rcp_f32_e32 v21, v21
	v_pk_mul_f32 v[8:9], v[8:9], v[16:17]
	v_mul_f32_e32 v16, 0xbfb8aa3b, v10
	v_mul_f32_e32 v17, 0xbfb8aa3b, v11
	v_exp_f32_e32 v16, v16
	v_exp_f32_e32 v17, v17
	v_pk_mul_f32 v[14:15], v[28:29], v[14:15]
	v_pk_mul_f32 v[6:7], v[104:105], v[6:7]
	v_pk_mul_f32 v[14:15], v[14:15], v[18:19] op_sel_hi:[1,0]
	v_pk_mul_f32 v[6:7], v[6:7], v[18:19] op_sel_hi:[1,0]
	v_pk_mul_f32 v[12:13], v[12:13], v[20:21]
	v_pk_mul_f32 v[2:3], v[2:3], v[18:19] op_sel_hi:[1,0]
	v_pk_mul_f32 v[6:7], v[6:7], v[12:13]
	v_add_f32_e32 v12, 1.0, v16
	v_add_f32_e32 v13, 1.0, v17
	v_mul_f32_e32 v16, 0xbfb8aa3b, v14
	v_mul_f32_e32 v17, 0xbfb8aa3b, v15
	v_exp_f32_e32 v16, v16
	v_exp_f32_e32 v17, v17
	v_rcp_f32_e32 v12, v12
	v_rcp_f32_e32 v13, v13
	v_add_f32_e32 v16, 1.0, v16
	v_add_f32_e32 v17, 1.0, v17
	v_rcp_f32_e32 v16, v16
	v_rcp_f32_e32 v17, v17
	v_pk_mul_f32 v[10:11], v[10:11], v[12:13]
	v_pk_mul_f32 v[4:5], v[42:43], v[4:5]
	v_pk_mul_f32 v[2:3], v[2:3], v[10:11]
	v_mov_b32_e32 v10, v139
	v_mov_b32_e32 v11, v139
	v_cvt_pk_fp8_f32 v10, v6, v7
	v_cvt_pk_fp8_f32 v11, v2, v3
	v_pk_mul_f32 v[4:5], v[4:5], v[18:19] op_sel_hi:[1,0]
	v_pk_mul_f32 v[2:3], v[14:15], v[16:17]
	v_cvt_pk_fp8_f32 v10, v8, v9 op_sel:[0,0,1]
	v_pk_mul_f32 v[2:3], v[4:5], v[2:3]
	s_nop 0
	v_cvt_pk_fp8_f32 v11, v2, v3 op_sel:[0,0,1]
	v_mad_i64_i32 v[2:3], s[30:31], v19, s58, v[116:117]
	v_lshl_add_u64 v[2:3], v[2:3], 0, s[28:29]
	v_lshl_add_u64 v[2:3], v[2:3], 0, v[138:139]
	global_store_dwordx2 v[2:3], v[10:11], off
	s_cbranch_vccnz .LBB0_2016
	s_andn2_b64 vcc, exec, s[10:11]
	s_cbranch_vccnz .LBB0_2015
	s_barrier
	s_branch .LBB0_2015
